# attention key loop: the four K-fragment LDS reads of the first QK^T block hoisted to the loop top (before the next tile's global loads) into free registers, counted lgkmcnt waits instead of read/wait/
# speedup vs baseline: 1.0032x; 1.0001x over previous
.LBB0_1800:
	s_and_b32 s98, s54, 1
	s_mul_i32 s98, s98, 0x4600
	v_lshl_or_b32 v236, s98, 1, v169
	v_add_u32_e32 v236, v236, v199
	ds_read_b128 v[220:223], v236
	ds_read_b128 v[224:227], v236 offset:32
	ds_read_b128 v[228:231], v236 offset:64
	ds_read_b128 v[232:235], v236 offset:96
	v_mul_u32_u24_e32 v0, s30, v194
	v_lshlrev_b32_e32 v0, 1, v0
	v_lshl_add_u64 v[2:3], s[38:39], 0, v[0:1]
	v_lshl_add_u64 v[6:7], v[2:3], 0, v[154:155]
	v_mul_u32_u24_e32 v0, s28, v183
	s_lshl_b32 s8, s30, 5
	v_lshlrev_b32_e32 v0, 1, v0
	v_lshl_add_u64 v[10:11], v[6:7], 0, s[8:9]
	v_lshl_add_u64 v[2:3], s[36:37], 0, v[0:1]
	v_lshl_add_u64 v[80:81], v[10:11], 0, s[8:9]
	v_lshl_add_u64 v[14:15], v[2:3], 0, v[150:151]
	global_load_dwordx4 v[2:5], v[6:7], off
	global_load_dwordx4 v[132:135], v[14:15], off
	s_nop 0
	global_load_dwordx4 v[6:9], v[10:11], off
	s_nop 0
	global_load_dwordx4 v[10:13], v[80:81], off
	v_lshl_add_u64 v[80:81], v[80:81], 0, s[8:9]
	s_lshl_b32 s8, s28, 6
	v_lshl_add_u64 v[14:15], v[14:15], 0, s[8:9]
	global_load_dwordx4 v[136:139], v[14:15], off
	v_lshl_add_u64 v[14:15], v[14:15], 0, s[8:9]
	global_load_dwordx4 v[140:143], v[14:15], off
	v_lshl_add_u64 v[14:15], v[14:15], 0, s[8:9]
	global_load_dwordx4 v[128:131], v[80:81], off
	global_load_dwordx4 v[144:147], v[14:15], off
	s_and_b32 s8, s54, 1
	s_mul_i32 s28, s8, 0x4600
	v_lshl_or_b32 v0, s28, 1, v169
	v_add_u32_e32 v14, v0, v199
	s_waitcnt lgkmcnt(3)
	v_mfma_f32_32x32x16_bf16 v[80:95], v[220:223], v[124:127], 0
	s_waitcnt lgkmcnt(2)
	v_mfma_f32_32x32x16_bf16 v[80:95], v[224:227], v[120:123], v[80:95]
	s_waitcnt lgkmcnt(1)
	v_mfma_f32_32x32x16_bf16 v[80:95], v[228:231], v[116:119], v[80:95]
	s_waitcnt lgkmcnt(0)
	v_mfma_f32_32x32x16_bf16 v[80:95], v[232:235], v[112:115], v[80:95]
	s_nop 11
	v_max_f32_e32 v0, v81, v81
	v_max_f32_e32 v15, v80, v80
	v_max_f32_e32 v0, v15, v0
	v_max3_f32 v0, v0, v82, v83
	v_max3_f32 v0, v0, v84, v85
	v_max3_f32 v0, v0, v86, v87
	v_max3_f32 v0, v0, v88, v89
	v_max3_f32 v0, v0, v90, v91
	v_max3_f32 v0, v0, v92, v93
	v_max3_f32 v0, v0, v94, v95
	v_mov_b32_e32 v15, v0
	s_nop 1
	v_permlane32_swap_b32_e32 v0, v15
	v_max3_f32 v0, v177, v0, v15
	v_cmp_gt_f32_e32 vcc, v0, v177
	s_cbranch_vccz .LBB0_1802
	v_sub_f32_e32 v15, v177, v0
	v_exp_f32_e32 v96, v15
	s_nop 0
	v_mul_f32_e32 v157, v157, v96
	v_pk_mul_f32 v[78:79], v[78:79], v[96:97] op_sel_hi:[1,0]
	v_pk_mul_f32 v[76:77], v[76:77], v[96:97] op_sel_hi:[1,0]
	v_pk_mul_f32 v[74:75], v[74:75], v[96:97] op_sel_hi:[1,0]
	v_pk_mul_f32 v[72:73], v[72:73], v[96:97] op_sel_hi:[1,0]
	v_pk_mul_f32 v[70:71], v[70:71], v[96:97] op_sel_hi:[1,0]
	v_pk_mul_f32 v[68:69], v[68:69], v[96:97] op_sel_hi:[1,0]
	v_pk_mul_f32 v[66:67], v[66:67], v[96:97] op_sel_hi:[1,0]
	v_pk_mul_f32 v[64:65], v[64:65], v[96:97] op_sel_hi:[1,0]
	v_pk_mul_f32 v[62:63], v[62:63], v[96:97] op_sel_hi:[1,0]
	v_pk_mul_f32 v[60:61], v[60:61], v[96:97] op_sel_hi:[1,0]
	v_pk_mul_f32 v[58:59], v[58:59], v[96:97] op_sel_hi:[1,0]
	v_pk_mul_f32 v[56:57], v[56:57], v[96:97] op_sel_hi:[1,0]
	v_pk_mul_f32 v[54:55], v[54:55], v[96:97] op_sel_hi:[1,0]
	v_pk_mul_f32 v[52:53], v[52:53], v[96:97] op_sel_hi:[1,0]
	v_pk_mul_f32 v[50:51], v[50:51], v[96:97] op_sel_hi:[1,0]
	v_pk_mul_f32 v[48:49], v[48:49], v[96:97] op_sel_hi:[1,0]
	v_pk_mul_f32 v[46:47], v[46:47], v[96:97] op_sel_hi:[1,0]
	v_pk_mul_f32 v[44:45], v[44:45], v[96:97] op_sel_hi:[1,0]
	v_pk_mul_f32 v[42:43], v[42:43], v[96:97] op_sel_hi:[1,0]
	v_pk_mul_f32 v[40:41], v[40:41], v[96:97] op_sel_hi:[1,0]
	v_pk_mul_f32 v[38:39], v[38:39], v[96:97] op_sel_hi:[1,0]
	v_pk_mul_f32 v[36:37], v[36:37], v[96:97] op_sel_hi:[1,0]
	v_pk_mul_f32 v[34:35], v[34:35], v[96:97] op_sel_hi:[1,0]
	v_pk_mul_f32 v[32:33], v[32:33], v[96:97] op_sel_hi:[1,0]
	v_pk_mul_f32 v[30:31], v[30:31], v[96:97] op_sel_hi:[1,0]
	v_pk_mul_f32 v[28:29], v[28:29], v[96:97] op_sel_hi:[1,0]
	v_pk_mul_f32 v[26:27], v[26:27], v[96:97] op_sel_hi:[1,0]
	v_pk_mul_f32 v[24:25], v[24:25], v[96:97] op_sel_hi:[1,0]
	v_pk_mul_f32 v[22:23], v[22:23], v[96:97] op_sel_hi:[1,0]
	v_pk_mul_f32 v[20:21], v[20:21], v[96:97] op_sel_hi:[1,0]
	v_pk_mul_f32 v[18:19], v[18:19], v[96:97] op_sel_hi:[1,0]
	v_pk_mul_f32 v[16:17], v[16:17], v[96:97] op_sel_hi:[1,0]
	s_branch .LBB0_1803
